# in-proj epilogue: removed the now-dead exec-masked address/readlane sections of blocks 2-8 (171 lines)
# speedup vs baseline: 1.0097x; 1.0097x over previous
; DEV unsigned short f2bf(float f) { return (unsigned short)(pack2(f, 0.f) & 0xFFFFu); }
; template <int EPI>
; __device__ void gemm_phase256(const Params& P, int l, const bf16_t* __restrict__ A, const bf16_t* __restrict__ Bt, int NT, char* smem) {
;     ...
; #pragma unroll
;       for (int mi = 0; mi < 4; ++mi)
; #pragma unroll
;         for (int ni = 0; ni < 2; ++ni) {
;           const int col = wn * 64 + ni * 32 + lr;
;           const int n = n0 + col;
;           const float bias = (EPI == 0) ? ((n < NIN) ? P.b_in[l * NIN + n] : 0.f) : 0.f;
;           const int rb = wm * 128 + mi * 32 + 4 * hk;
; #pragma unroll
;           for (int i = 0; i < 16; ++i) Cs[(rb + (i & 3) + 8 * (i >> 2)) * 136 + col] = f2bf(acc[mi][ni][i] + bias);
;         }
.Lipb_bias1_done:
	s_or_b64 exec, exec, s[38:39]
	s_waitcnt vmcnt(0)
	v_mov_b32_e32 v140, v129
	v_mov_b32_e32 v141, v130
	v_add_f32_e32 v131, v112, v129
	v_cvt_pk_bf16_f32 v131, v131, s0
	ds_write_b16 v228, v131
	v_add_f32_e32 v131, v113, v129
	v_cvt_pk_bf16_f32 v131, v131, s0
	ds_write_b16 v228, v131 offset:272
	v_add_f32_e32 v131, v114, v129
	v_cvt_pk_bf16_f32 v131, v131, s0
	ds_write_b16 v228, v131 offset:544
	v_add_f32_e32 v131, v115, v129
	v_cvt_pk_bf16_f32 v131, v131, s0
	ds_write_b16 v228, v131 offset:816
	v_add_f32_e32 v131, v116, v129
	v_cvt_pk_bf16_f32 v131, v131, s0
	ds_write_b16 v228, v131 offset:2176
	v_add_f32_e32 v131, v117, v129
	v_cvt_pk_bf16_f32 v131, v131, s0
	ds_write_b16 v228, v131 offset:2448
	v_add_f32_e32 v131, v118, v129
	v_cvt_pk_bf16_f32 v131, v131, s0
	ds_write_b16 v228, v131 offset:2720
	v_add_f32_e32 v131, v119, v129
	v_cvt_pk_bf16_f32 v131, v131, s0
	ds_write_b16 v228, v131 offset:2992
	v_add_f32_e32 v131, v120, v129
	v_cvt_pk_bf16_f32 v131, v131, s0
	ds_write_b16 v228, v131 offset:4352
	v_add_f32_e32 v131, v121, v129
	v_cvt_pk_bf16_f32 v131, v131, s0
	ds_write_b16 v228, v131 offset:4624
	v_add_f32_e32 v131, v122, v129
	v_cvt_pk_bf16_f32 v131, v131, s0
	ds_write_b16 v228, v131 offset:4896
	v_add_f32_e32 v131, v123, v129
	v_cvt_pk_bf16_f32 v131, v131, s0
	ds_write_b16 v228, v131 offset:5168
	v_add_f32_e32 v131, v124, v129
	v_cvt_pk_bf16_f32 v131, v131, s0
	ds_write_b16 v228, v131 offset:6528
	v_add_f32_e32 v131, v125, v129
	v_cvt_pk_bf16_f32 v131, v131, s0
	ds_write_b16 v228, v131 offset:6800
	v_add_f32_e32 v131, v126, v129
	v_add_f32_e32 v129, v127, v129
	v_cvt_pk_bf16_f32 v129, v129, s0
	ds_write_b16 v228, v129 offset:7344
	v_cvt_pk_bf16_f32 v131, v131, s0
	ds_write_b16 v228, v131 offset:7072
	v_mov_b32_e32 v130, v141
	v_add_f32_e32 v129, v96, v130
	v_cvt_pk_bf16_f32 v129, v129, s0
	ds_write_b16 v228, v129 offset:64
	v_add_f32_e32 v129, v97, v130
	v_cvt_pk_bf16_f32 v129, v129, s0
	ds_write_b16 v228, v129 offset:336
	v_add_f32_e32 v129, v98, v130
	v_cvt_pk_bf16_f32 v129, v129, s0
	ds_write_b16 v228, v129 offset:608
	v_add_f32_e32 v129, v99, v130
	v_cvt_pk_bf16_f32 v129, v129, s0
	ds_write_b16 v228, v129 offset:880
	v_add_f32_e32 v129, v100, v130
	v_cvt_pk_bf16_f32 v129, v129, s0
	ds_write_b16 v228, v129 offset:2240
	v_add_f32_e32 v129, v101, v130
	v_cvt_pk_bf16_f32 v129, v129, s0
	ds_write_b16 v228, v129 offset:2512
	v_add_f32_e32 v129, v102, v130
	v_cvt_pk_bf16_f32 v129, v129, s0
	ds_write_b16 v228, v129 offset:2784
	v_add_f32_e32 v129, v103, v130
	v_cvt_pk_bf16_f32 v129, v129, s0
	ds_write_b16 v228, v129 offset:3056
	v_add_f32_e32 v129, v104, v130
	v_cvt_pk_bf16_f32 v129, v129, s0
	ds_write_b16 v228, v129 offset:4416
	v_add_f32_e32 v129, v105, v130
	v_cvt_pk_bf16_f32 v129, v129, s0
	ds_write_b16 v228, v129 offset:4688
	v_add_f32_e32 v129, v106, v130
	v_cvt_pk_bf16_f32 v129, v129, s0
	ds_write_b16 v228, v129 offset:4960
	v_add_f32_e32 v129, v107, v130
	v_cvt_pk_bf16_f32 v129, v129, s0
	ds_write_b16 v228, v129 offset:5232
	v_add_f32_e32 v129, v108, v130
	v_cvt_pk_bf16_f32 v129, v129, s0
	ds_write_b16 v228, v129 offset:6592
	v_add_f32_e32 v129, v109, v130
	v_cvt_pk_bf16_f32 v129, v129, s0
	ds_write_b16 v228, v129 offset:6864
	v_add_f32_e32 v129, v110, v130
	v_cvt_pk_bf16_f32 v129, v129, s0
	ds_write_b16 v228, v129 offset:7136
	v_add_f32_e32 v129, v111, v130
	v_cvt_pk_bf16_f32 v129, v129, s0
	ds_write_b16 v228, v129 offset:7408
	v_mov_b32_e32 v129, v140
	v_add_f32_e32 v131, v80, v129
	v_cvt_pk_bf16_f32 v131, v131, s0
	ds_write_b16 v228, v131 offset:8704
	v_add_f32_e32 v131, v81, v129
	v_cvt_pk_bf16_f32 v131, v131, s0
	ds_write_b16 v228, v131 offset:8976
	v_add_f32_e32 v131, v82, v129
	v_cvt_pk_bf16_f32 v131, v131, s0
	ds_write_b16 v228, v131 offset:9248
	v_add_f32_e32 v131, v83, v129
	v_cvt_pk_bf16_f32 v131, v131, s0
	ds_write_b16 v228, v131 offset:9520
	v_add_f32_e32 v131, v84, v129
	v_cvt_pk_bf16_f32 v131, v131, s0
	ds_write_b16 v228, v131 offset:10880
	v_add_f32_e32 v131, v85, v129
	v_cvt_pk_bf16_f32 v131, v131, s0
	ds_write_b16 v228, v131 offset:11152
	v_add_f32_e32 v131, v86, v129
	v_cvt_pk_bf16_f32 v131, v131, s0
	ds_write_b16 v228, v131 offset:11424
	v_add_f32_e32 v131, v87, v129
	v_cvt_pk_bf16_f32 v131, v131, s0
	ds_write_b16 v228, v131 offset:11696
	v_add_f32_e32 v131, v88, v129
	v_cvt_pk_bf16_f32 v131, v131, s0
	ds_write_b16 v228, v131 offset:13056
	v_add_f32_e32 v131, v89, v129
	v_cvt_pk_bf16_f32 v131, v131, s0
	ds_write_b16 v228, v131 offset:13328
	v_add_f32_e32 v131, v90, v129
	v_cvt_pk_bf16_f32 v131, v131, s0
	ds_write_b16 v228, v131 offset:13600
	v_add_f32_e32 v131, v91, v129
	v_cvt_pk_bf16_f32 v131, v131, s0
	ds_write_b16 v228, v131 offset:13872
	v_add_f32_e32 v131, v92, v129
	v_cvt_pk_bf16_f32 v131, v131, s0
	ds_write_b16 v228, v131 offset:15232
	v_add_f32_e32 v131, v93, v129
	v_cvt_pk_bf16_f32 v131, v131, s0
	ds_write_b16 v228, v131 offset:15504
	v_add_f32_e32 v131, v94, v129
	v_add_f32_e32 v129, v95, v129
	v_cvt_pk_bf16_f32 v131, v131, s0
	v_cvt_pk_bf16_f32 v129, v129, s0
	ds_write_b16 v228, v131 offset:15776
	ds_write_b16 v228, v129 offset:16048
	v_mov_b32_e32 v130, v141
	v_add_f32_e32 v129, v64, v130
	v_cvt_pk_bf16_f32 v129, v129, s0
	ds_write_b16 v228, v129 offset:8768
	v_add_f32_e32 v129, v65, v130
	v_cvt_pk_bf16_f32 v129, v129, s0
	ds_write_b16 v228, v129 offset:9040
	v_add_f32_e32 v129, v66, v130
	v_cvt_pk_bf16_f32 v129, v129, s0
	ds_write_b16 v228, v129 offset:9312
	v_add_f32_e32 v129, v67, v130
	v_cvt_pk_bf16_f32 v129, v129, s0
	ds_write_b16 v228, v129 offset:9584
	v_add_f32_e32 v129, v68, v130
	v_cvt_pk_bf16_f32 v129, v129, s0
	ds_write_b16 v228, v129 offset:10944
; DEV unsigned short f2bf(float f) { return (unsigned short)(pack2(f, 0.f) & 0xFFFFu); }
; template <int EPI>
; __device__ void gemm_phase256(const Params& P, int l, const bf16_t* __restrict__ A, const bf16_t* __restrict__ Bt, int NT, char* smem) {
;     ...
; #pragma unroll
;       for (int mi = 0; mi < 4; ++mi)
; #pragma unroll
;         for (int ni = 0; ni < 2; ++ni) {
;           const int col = wn * 64 + ni * 32 + lr;
;           const int n = n0 + col;
;           const float bias = (EPI == 0) ? ((n < NIN) ? P.b_in[l * NIN + n] : 0.f) : 0.f;
;           const int rb = wm * 128 + mi * 32 + 4 * hk;
; #pragma unroll
;           for (int i = 0; i < 16; ++i) Cs[(rb + (i & 3) + 8 * (i >> 2)) * 136 + col] = f2bf(acc[mi][ni][i] + bias);
;         }
	v_add_f32_e32 v129, v69, v130
	v_cvt_pk_bf16_f32 v129, v129, s0
	ds_write_b16 v228, v129 offset:11216
	v_add_f32_e32 v129, v70, v130
	v_cvt_pk_bf16_f32 v129, v129, s0
	ds_write_b16 v228, v129 offset:11488
	v_add_f32_e32 v129, v71, v130
	v_cvt_pk_bf16_f32 v129, v129, s0
	ds_write_b16 v228, v129 offset:11760
	v_add_f32_e32 v129, v72, v130
	v_cvt_pk_bf16_f32 v129, v129, s0
	ds_write_b16 v228, v129 offset:13120
	v_add_f32_e32 v129, v73, v130
	v_cvt_pk_bf16_f32 v129, v129, s0
	ds_write_b16 v228, v129 offset:13392
	v_add_f32_e32 v129, v74, v130
	v_cvt_pk_bf16_f32 v129, v129, s0
	ds_write_b16 v228, v129 offset:13664
	v_add_f32_e32 v129, v75, v130
	v_cvt_pk_bf16_f32 v129, v129, s0
	ds_write_b16 v228, v129 offset:13936
	v_add_f32_e32 v129, v76, v130
	v_cvt_pk_bf16_f32 v129, v129, s0
	ds_write_b16 v228, v129 offset:15296
	v_add_f32_e32 v129, v77, v130
	v_cvt_pk_bf16_f32 v129, v129, s0
	ds_write_b16 v228, v129 offset:15568
	v_add_f32_e32 v129, v78, v130
	v_cvt_pk_bf16_f32 v129, v129, s0
	ds_write_b16 v228, v129 offset:15840
	v_add_f32_e32 v129, v79, v130
	v_cvt_pk_bf16_f32 v129, v129, s0
	ds_write_b16 v228, v129 offset:16112
	v_mov_b32_e32 v129, v140
	v_add_f32_e32 v131, v48, v129
	v_cvt_pk_bf16_f32 v131, v131, s0
	ds_write_b16 v228, v131 offset:17408
	v_add_f32_e32 v131, v49, v129
	v_cvt_pk_bf16_f32 v131, v131, s0
	ds_write_b16 v228, v131 offset:17680
	v_add_f32_e32 v131, v50, v129
	v_cvt_pk_bf16_f32 v131, v131, s0
	ds_write_b16 v228, v131 offset:17952
	v_add_f32_e32 v131, v51, v129
	v_cvt_pk_bf16_f32 v131, v131, s0
	ds_write_b16 v228, v131 offset:18224
	v_add_f32_e32 v131, v52, v129
	v_cvt_pk_bf16_f32 v131, v131, s0
	ds_write_b16 v228, v131 offset:19584
	v_add_f32_e32 v131, v53, v129
	v_cvt_pk_bf16_f32 v131, v131, s0
	ds_write_b16 v228, v131 offset:19856
	v_add_f32_e32 v131, v54, v129
	v_cvt_pk_bf16_f32 v131, v131, s0
	ds_write_b16 v228, v131 offset:20128
	v_add_f32_e32 v131, v55, v129
	v_cvt_pk_bf16_f32 v131, v131, s0
	ds_write_b16 v228, v131 offset:20400
	v_add_f32_e32 v131, v56, v129
	v_cvt_pk_bf16_f32 v131, v131, s0
	ds_write_b16 v228, v131 offset:21760
	v_add_f32_e32 v131, v57, v129
	v_cvt_pk_bf16_f32 v131, v131, s0
	ds_write_b16 v228, v131 offset:22032
	v_add_f32_e32 v131, v58, v129
	v_cvt_pk_bf16_f32 v131, v131, s0
	ds_write_b16 v228, v131 offset:22304
	v_add_f32_e32 v131, v59, v129
	v_cvt_pk_bf16_f32 v131, v131, s0
	ds_write_b16 v228, v131 offset:22576
	v_add_f32_e32 v131, v60, v129
	v_cvt_pk_bf16_f32 v131, v131, s0
	ds_write_b16 v228, v131 offset:23936
	v_add_f32_e32 v131, v61, v129
	v_cvt_pk_bf16_f32 v131, v131, s0
	ds_write_b16 v228, v131 offset:24208
	v_add_f32_e32 v131, v62, v129
	v_add_f32_e32 v129, v63, v129
	v_cvt_pk_bf16_f32 v131, v131, s0
	v_cvt_pk_bf16_f32 v129, v129, s0
	ds_write_b16 v228, v131 offset:24480
	ds_write_b16 v228, v129 offset:24752
	v_mov_b32_e32 v130, v141
	v_add_f32_e32 v129, v32, v130
	v_cvt_pk_bf16_f32 v129, v129, s0
	ds_write_b16 v228, v129 offset:17472
	v_add_f32_e32 v129, v33, v130
	v_cvt_pk_bf16_f32 v129, v129, s0
	ds_write_b16 v228, v129 offset:17744
	v_add_f32_e32 v129, v34, v130
	v_cvt_pk_bf16_f32 v129, v129, s0
	ds_write_b16 v228, v129 offset:18016
	v_add_f32_e32 v129, v35, v130
	v_cvt_pk_bf16_f32 v129, v129, s0
	ds_write_b16 v228, v129 offset:18288
	v_add_f32_e32 v129, v36, v130
	v_cvt_pk_bf16_f32 v129, v129, s0
	ds_write_b16 v228, v129 offset:19648
	v_add_f32_e32 v129, v37, v130
	v_cvt_pk_bf16_f32 v129, v129, s0
	ds_write_b16 v228, v129 offset:19920
	v_add_f32_e32 v129, v38, v130
	v_cvt_pk_bf16_f32 v129, v129, s0
	ds_write_b16 v228, v129 offset:20192
	v_add_f32_e32 v129, v39, v130
	v_cvt_pk_bf16_f32 v129, v129, s0
	ds_write_b16 v228, v129 offset:20464
	v_add_f32_e32 v129, v40, v130
	v_cvt_pk_bf16_f32 v129, v129, s0
	ds_write_b16 v228, v129 offset:21824
	v_add_f32_e32 v129, v41, v130
	v_cvt_pk_bf16_f32 v129, v129, s0
	ds_write_b16 v228, v129 offset:22096
	v_add_f32_e32 v129, v42, v130
	v_cvt_pk_bf16_f32 v129, v129, s0
	ds_write_b16 v228, v129 offset:22368
	v_add_f32_e32 v129, v43, v130
	v_cvt_pk_bf16_f32 v129, v129, s0
	ds_write_b16 v228, v129 offset:22640
; DEV unsigned short f2bf(float f) { return (unsigned short)(pack2(f, 0.f) & 0xFFFFu); }
; template <int EPI>
; __device__ void gemm_phase256(const Params& P, int l, const bf16_t* __restrict__ A, const bf16_t* __restrict__ Bt, int NT, char* smem) {
;     ...
;           const int col = wn * 64 + ni * 32 + lr;
;           const int n = n0 + col;
;           const float bias = (EPI == 0) ? ((n < NIN) ? P.b_in[l * NIN + n] : 0.f) : 0.f;
;           const int rb = wm * 128 + mi * 32 + 4 * hk;
; #pragma unroll
;           for (int i = 0; i < 16; ++i) Cs[(rb + (i & 3) + 8 * (i >> 2)) * 136 + col] = f2bf(acc[mi][ni][i] + bias);
;         }
;       __syncthreads();
;       bf16_t* dstb; int dstride, cbase, nvalid;
;       if (EPI == 0) { dstb = P.H; dstride = HS; cbase = n0 - (nt == 16 ? 128 : (nt == 18 ? 256 : 0)); nvalid = (NIN - n0 < 128) ? (NIN - n0) : 128; }
	v_add_f32_e32 v129, v44, v130
	v_cvt_pk_bf16_f32 v129, v129, s0
	ds_write_b16 v228, v129 offset:24000
	v_add_f32_e32 v129, v45, v130
	v_cvt_pk_bf16_f32 v129, v129, s0
	ds_write_b16 v228, v129 offset:24272
	v_add_f32_e32 v129, v46, v130
	v_cvt_pk_bf16_f32 v129, v129, s0
	ds_write_b16 v228, v129 offset:24544
	v_add_f32_e32 v129, v47, v130
	v_cvt_pk_bf16_f32 v129, v129, s0
	ds_write_b16 v228, v129 offset:24816
	v_mov_b32_e32 v129, v140
	v_add_f32_e32 v128, v16, v129
	v_cvt_pk_bf16_f32 v128, v128, s0
	ds_write_b16 v228, v128 offset:26112
	v_add_f32_e32 v128, v17, v129
	v_cvt_pk_bf16_f32 v128, v128, s0
	ds_write_b16 v228, v128 offset:26384
	v_add_f32_e32 v128, v18, v129
	v_cvt_pk_bf16_f32 v128, v128, s0
	ds_write_b16 v228, v128 offset:26656
	v_add_f32_e32 v128, v19, v129
	v_cvt_pk_bf16_f32 v128, v128, s0
	ds_write_b16 v228, v128 offset:26928
	v_add_f32_e32 v128, v20, v129
	v_cvt_pk_bf16_f32 v128, v128, s0
	ds_write_b16 v228, v128 offset:28288
	v_add_f32_e32 v128, v21, v129
	v_cvt_pk_bf16_f32 v128, v128, s0
	ds_write_b16 v228, v128 offset:28560
	v_add_f32_e32 v128, v22, v129
	v_cvt_pk_bf16_f32 v128, v128, s0
	ds_write_b16 v228, v128 offset:28832
	v_add_f32_e32 v128, v23, v129
	v_cvt_pk_bf16_f32 v128, v128, s0
	ds_write_b16 v228, v128 offset:29104
	v_add_f32_e32 v128, v24, v129
	v_cvt_pk_bf16_f32 v128, v128, s0
	ds_write_b16 v228, v128 offset:30464
	v_add_f32_e32 v128, v25, v129
	v_cvt_pk_bf16_f32 v128, v128, s0
	ds_write_b16 v228, v128 offset:30736
	v_add_f32_e32 v128, v26, v129
	v_cvt_pk_bf16_f32 v128, v128, s0
	ds_write_b16 v228, v128 offset:31008
	v_add_f32_e32 v128, v27, v129
	v_cvt_pk_bf16_f32 v128, v128, s0
	ds_write_b16 v228, v128 offset:31280
	v_add_f32_e32 v128, v28, v129
	v_cvt_pk_bf16_f32 v128, v128, s0
	ds_write_b16 v228, v128 offset:32640
	v_add_f32_e32 v128, v29, v129
	v_cvt_pk_bf16_f32 v128, v128, s0
	ds_write_b16 v228, v128 offset:32912
	v_add_f32_e32 v128, v30, v129
	v_cvt_pk_bf16_f32 v128, v128, s0
	ds_write_b16 v228, v128 offset:33184
	v_add_f32_e32 v128, v31, v129
	v_cvt_pk_bf16_f32 v128, v128, s0
	ds_write_b16 v228, v128 offset:33456
	v_mov_b32_e32 v130, v141
	v_add_f32_e32 v128, v0, v130
	v_cvt_pk_bf16_f32 v128, v128, s0
	ds_write_b16 v228, v128 offset:26176
	v_add_f32_e32 v128, v1, v130
	v_cvt_pk_bf16_f32 v128, v128, s0
	ds_write_b16 v228, v128 offset:26448
	v_add_f32_e32 v128, v2, v130
	v_cvt_pk_bf16_f32 v128, v128, s0
	ds_write_b16 v228, v128 offset:26720
	v_add_f32_e32 v128, v3, v130
	v_cvt_pk_bf16_f32 v128, v128, s0
	ds_write_b16 v228, v128 offset:26992
	v_add_f32_e32 v128, v4, v130
	v_cvt_pk_bf16_f32 v128, v128, s0
	ds_write_b16 v228, v128 offset:28352
	v_add_f32_e32 v128, v5, v130
	v_cvt_pk_bf16_f32 v128, v128, s0
	ds_write_b16 v228, v128 offset:28624
	v_add_f32_e32 v128, v6, v130
	v_cvt_pk_bf16_f32 v128, v128, s0
	ds_write_b16 v228, v128 offset:28896
	v_add_f32_e32 v128, v7, v130
	v_cvt_pk_bf16_f32 v128, v128, s0
	ds_write_b16 v228, v128 offset:29168
	v_add_f32_e32 v128, v8, v130
	v_cvt_pk_bf16_f32 v128, v128, s0
	ds_write_b16 v228, v128 offset:30528
	v_add_f32_e32 v128, v9, v130
	v_cvt_pk_bf16_f32 v128, v128, s0
	ds_write_b16 v228, v128 offset:30800
	v_add_f32_e32 v128, v10, v130
	v_cvt_pk_bf16_f32 v128, v128, s0
	ds_write_b16 v228, v128 offset:31072
	v_add_f32_e32 v128, v11, v130
	v_cvt_pk_bf16_f32 v128, v128, s0
	ds_write_b16 v228, v128 offset:31344
	v_add_f32_e32 v128, v12, v130
	v_cvt_pk_bf16_f32 v128, v128, s0
	ds_write_b16 v228, v128 offset:32704
	v_add_f32_e32 v128, v13, v130
	v_cvt_pk_bf16_f32 v128, v128, s0
	s_cmp_eq_u32 s33, 18
	ds_write_b16 v228, v128 offset:32976
	v_add_f32_e32 v128, v14, v130
	s_cselect_b32 s37, 0xffffff00, 0
	s_cmp_lg_u32 s33, 16
	v_cvt_pk_bf16_f32 v128, v128, s0
	s_cselect_b32 s37, s37, 0xffffff80
	ds_write_b16 v228, v128 offset:33248
	v_add_f32_e32 v128, v15, v130
	s_add_i32 s38, s37, s0
	v_cvt_pk_bf16_f32 v128, v128, s0
	s_ashr_i32 s39, s38, 31
	ds_write_b16 v228, v128 offset:33520
	s_mov_b32 s1, 0
	v_cmp_lt_i32_e32 vcc, s0, v185
	v_lshl_add_u64 v[128:129], s[38:39], 1, v[192:193]
	s_waitcnt lgkmcnt(0)
	s_barrier
	s_branch .LBB0_265
